# v73 plus vmcnt(0)/lgkmcnt(0) drain before the staging entry barrier (no stale LDS-DMA from the preceding GEMM can land in the staging area)
# baseline (speedup 1.0000x reference)
.LBB0_125:
	s_mul_hi_i32 s28, s61, 0x2aaaaaab
	s_lshr_b32 s29, s28, 31
	s_ashr_i32 s28, s28, 3
	s_add_i32 s31, s28, s29
	s_mul_i32 s28, s31, 0xffffffd0
	s_add_i32 s63, s61, s28
	s_mul_i32 s28, s31, 0xfffff400
	s_add_i32 s30, s27, s28
	s_and_b32 s28, s30, 0xffffff00
	s_and_b32 s29, s54, 0x60
	s_or_b32 s28, s28, s29
	s_ashr_i32 s29, s28, 31
	s_lshl_b64 s[34:35], s[28:29], 11
	s_add_u32 s34, s3, s34
	s_addc_u32 s35, s39, s35
	s_bitset1_b32 s28, 7
	s_ashr_i32 s29, s28, 31
	v_mov_b32_e32 v37, v228
	s_lshl_b64 s[28:29], s[28:29], 11
	s_add_u32 s36, s3, s28
	v_and_b32_e32 v122, 31, v37
	v_ashrrev_i32_e32 v123, 5, v37
	s_addc_u32 s37, s39, s29
	s_lshl_b32 s28, s31, 5
	s_ashr_i32 s29, s28, 31
	s_lshl_b64 s[64:65], s[28:29], 11
	s_add_u32 s64, s58, s64
	s_addc_u32 s65, s59, s65
	s_waitcnt vmcnt(0) lgkmcnt(0)
	s_barrier
	s_mov_b32 s101, m0
	s_mul_i32 s100, s2, 0x180
	v_lshrrev_b32_e32 v14, 2, v37
	v_bfe_u32 v15, v37, 4, 2
	v_lshlrev_b32_e32 v14, 11, v14
	v_xor_b32_e32 v15, v15, v37
	v_bfe_u32 v16, v122, 2, 2
	v_and_b32_e32 v15, 3, v15
	v_xor_b32_e32 v16, v16, v123
	v_lshl_or_b32 v14, v15, 4, v14
	v_lshlrev_b32_e32 v16, 4, v16
	v_lshl_or_b32 v15, v122, 6, v16
	v_add_u32_e32 v15, s100, v15
	v_xor_b32_e32 v16, 32, v15
	s_add_u32 s98, s34, s0
	s_addc_u32 s99, s35, 0
	s_add_i32 m0, s100, 0x0
	s_nop 0
	global_load_lds_dwordx4 v14, s[98:99]
	s_add_u32 s98, s34, s0
	s_addc_u32 s99, s35, 0
	s_add_u32 s98, s98, 0x8000
	s_addc_u32 s99, s99, 0
	s_add_i32 m0, s100, 0x400
	s_nop 0
	global_load_lds_dwordx4 v14, s[98:99]
	s_add_u32 s98, s36, s0
	s_addc_u32 s99, s37, 0
	s_add_i32 m0, s100, 0x800
	s_nop 0
	global_load_lds_dwordx4 v14, s[98:99]
	s_add_u32 s98, s36, s0
	s_addc_u32 s99, s37, 0
	s_add_u32 s98, s98, 0x8000
	s_addc_u32 s99, s99, 0
	s_add_i32 m0, s100, 0xc00
	s_nop 0
	global_load_lds_dwordx4 v14, s[98:99]
	s_add_u32 s98, s64, s0
	s_addc_u32 s99, s65, 0
	s_add_u32 s98, s98, 0x2000000
	s_addc_u32 s99, s99, 0
	s_add_i32 m0, s100, 0x1000
	s_nop 0
	global_load_lds_dwordx4 v14, s[98:99]
	s_add_u32 s98, s64, s0
	s_addc_u32 s99, s65, 0
	s_add_u32 s98, s98, 0x2008000
	s_addc_u32 s99, s99, 0
	s_add_i32 m0, s100, 0x1400
	s_nop 0
	global_load_lds_dwordx4 v14, s[98:99]
	s_add_u32 s98, s34, s0
	s_addc_u32 s99, s35, 0
	s_add_u32 s98, s98, 0x40
	s_addc_u32 s99, s99, 0
	s_add_i32 m0, s100, 0x1800
	s_nop 0
	global_load_lds_dwordx4 v14, s[98:99]
	s_add_u32 s98, s34, s0
	s_addc_u32 s99, s35, 0
	s_add_u32 s98, s98, 0x8040
	s_addc_u32 s99, s99, 0
	s_add_i32 m0, s100, 0x1c00
	s_nop 0
	global_load_lds_dwordx4 v14, s[98:99]
	s_add_u32 s98, s36, s0
	s_addc_u32 s99, s37, 0
	s_add_u32 s98, s98, 0x40
	s_addc_u32 s99, s99, 0
	s_add_i32 m0, s100, 0x2000
	s_nop 0
	global_load_lds_dwordx4 v14, s[98:99]
	s_add_u32 s98, s36, s0
	s_addc_u32 s99, s37, 0
	s_add_u32 s98, s98, 0x8040
	s_addc_u32 s99, s99, 0
	s_add_i32 m0, s100, 0x2400
	s_nop 0
	global_load_lds_dwordx4 v14, s[98:99]
	s_add_u32 s98, s64, s0
	s_addc_u32 s99, s65, 0
	s_add_u32 s98, s98, 0x2000040
	s_addc_u32 s99, s99, 0
	s_add_i32 m0, s100, 0x2800
	s_nop 0
	global_load_lds_dwordx4 v14, s[98:99]
	s_add_u32 s98, s64, s0
	s_addc_u32 s99, s65, 0
	s_add_u32 s98, s98, 0x2008040
	s_addc_u32 s99, s99, 0
	s_add_i32 m0, s100, 0x2c00
	s_nop 0
	global_load_lds_dwordx4 v14, s[98:99]
	s_waitcnt vmcnt(6)
	ds_read_b128 v[2:5], v15
	ds_read_b128 v[6:9], v15 offset:2048
	ds_read_b128 v[10:13], v15 offset:4096
	ds_read_b128 v[38:41], v16
	ds_read_b128 v[42:45], v16 offset:2048
	ds_read_b128 v[46:49], v16 offset:4096
	s_waitcnt lgkmcnt(0)
	s_add_u32 s98, s34, s0
	s_addc_u32 s99, s35, 0
	s_add_u32 s98, s98, 0x80
	s_addc_u32 s99, s99, 0
	s_add_i32 m0, s100, 0x0
	s_nop 0
	global_load_lds_dwordx4 v14, s[98:99]
	s_add_u32 s98, s34, s0
	s_addc_u32 s99, s35, 0
	s_add_u32 s98, s98, 0x8080
	s_addc_u32 s99, s99, 0
	s_add_i32 m0, s100, 0x400
	s_nop 0
	global_load_lds_dwordx4 v14, s[98:99]
	s_add_u32 s98, s36, s0
	s_addc_u32 s99, s37, 0
	s_add_u32 s98, s98, 0x80
	s_addc_u32 s99, s99, 0
	s_add_i32 m0, s100, 0x800
	s_nop 0
	global_load_lds_dwordx4 v14, s[98:99]
	s_add_u32 s98, s36, s0
	s_addc_u32 s99, s37, 0
	s_add_u32 s98, s98, 0x8080
	s_addc_u32 s99, s99, 0
	s_add_i32 m0, s100, 0xc00
	s_nop 0
	global_load_lds_dwordx4 v14, s[98:99]
	s_add_u32 s98, s64, s0
	s_addc_u32 s99, s65, 0
	s_add_u32 s98, s98, 0x2000080
	s_addc_u32 s99, s99, 0
	s_add_i32 m0, s100, 0x1000
	s_nop 0
	global_load_lds_dwordx4 v14, s[98:99]
	s_add_u32 s98, s64, s0
	s_addc_u32 s99, s65, 0
	s_add_u32 s98, s98, 0x2008080
	s_addc_u32 s99, s99, 0
	s_add_i32 m0, s100, 0x1400
	s_nop 0
	global_load_lds_dwordx4 v14, s[98:99]
	s_waitcnt vmcnt(6)
	ds_read_b128 v[54:57], v15 offset:6144
	ds_read_b128 v[62:65], v15 offset:8192
	ds_read_b128 v[50:53], v15 offset:10240
	ds_read_b128 v[58:61], v16 offset:6144
	ds_read_b128 v[66:69], v16 offset:8192
	ds_read_b128 v[70:73], v16 offset:10240
	s_waitcnt lgkmcnt(0)
	s_add_u32 s98, s34, s0
	s_addc_u32 s99, s35, 0
	s_add_u32 s98, s98, 0xc0
	s_addc_u32 s99, s99, 0
	s_add_i32 m0, s100, 0x1800
	s_nop 0
	global_load_lds_dwordx4 v14, s[98:99]
	s_add_u32 s98, s34, s0
	s_addc_u32 s99, s35, 0
	s_add_u32 s98, s98, 0x80c0
	s_addc_u32 s99, s99, 0
	s_add_i32 m0, s100, 0x1c00
	s_nop 0
	global_load_lds_dwordx4 v14, s[98:99]
	s_add_u32 s98, s36, s0
	s_addc_u32 s99, s37, 0
	s_add_u32 s98, s98, 0xc0
	s_addc_u32 s99, s99, 0
	s_add_i32 m0, s100, 0x2000
	s_nop 0
	global_load_lds_dwordx4 v14, s[98:99]
	s_add_u32 s98, s36, s0
	s_addc_u32 s99, s37, 0
	s_add_u32 s98, s98, 0x80c0
	s_addc_u32 s99, s99, 0
	s_add_i32 m0, s100, 0x2400
	s_nop 0
	global_load_lds_dwordx4 v14, s[98:99]
	s_add_u32 s98, s64, s0
	s_addc_u32 s99, s65, 0
	s_add_u32 s98, s98, 0x20000c0
	s_addc_u32 s99, s99, 0
	s_add_i32 m0, s100, 0x2800
	s_nop 0
	global_load_lds_dwordx4 v14, s[98:99]
	s_add_u32 s98, s64, s0
	s_addc_u32 s99, s65, 0
	s_add_u32 s98, s98, 0x20080c0
	s_addc_u32 s99, s99, 0
	s_add_i32 m0, s100, 0x2c00
	s_nop 0
	global_load_lds_dwordx4 v14, s[98:99]
	s_waitcnt vmcnt(6)
	ds_read_b128 v[78:81], v15
	ds_read_b128 v[86:89], v15 offset:2048
	ds_read_b128 v[74:77], v15 offset:4096
	ds_read_b128 v[82:85], v16
	ds_read_b128 v[90:93], v16 offset:2048
	ds_read_b128 v[94:97], v16 offset:4096
	s_waitcnt vmcnt(0)
	ds_read_b128 v[102:105], v15 offset:6144
	ds_read_b128 v[110:113], v15 offset:8192
	ds_read_b128 v[98:101], v15 offset:10240
	ds_read_b128 v[106:109], v16 offset:6144
	ds_read_b128 v[114:117], v16 offset:8192
	ds_read_b128 v[118:121], v16 offset:10240
	s_mov_b32 m0, s101
	s_waitcnt lgkmcnt(0)
	v_mfma_f32_32x32x16_bf16 v[18:33], v[2:5], v[10:13], 0
	v_or_b32_e32 v34, s2, v122
	v_mul_lo_u32 v34, v34, s57
	s_ashr_i32 s64, s63, 3
	v_mfma_f32_32x32x16_bf16 v[2:17], v[6:9], v[10:13], 0
	v_mfma_f32_32x32x16_bf16 v[18:33], v[38:41], v[46:49], v[18:33]
	v_lshlrev_b32_e32 v38, 4, v123
	v_add3_u32 v34, 0, v34, v38
	v_mfma_f32_32x32x16_bf16 v[2:17], v[42:45], v[46:49], v[2:17]
	v_mfma_f32_32x32x16_bf16 v[18:33], v[54:57], v[50:53], v[18:33]
	v_mfma_f32_32x32x16_bf16 v[2:17], v[62:65], v[50:53], v[2:17]
	v_mfma_f32_32x32x16_bf16 v[18:33], v[58:61], v[70:73], v[18:33]
	v_mfma_f32_32x32x16_bf16 v[2:17], v[66:69], v[70:73], v[2:17]
	v_mfma_f32_32x32x16_bf16 v[18:33], v[78:81], v[74:77], v[18:33]
	v_mfma_f32_32x32x16_bf16 v[2:17], v[86:89], v[74:77], v[2:17]
	v_mfma_f32_32x32x16_bf16 v[18:33], v[82:85], v[94:97], v[18:33]
	v_mfma_f32_32x32x16_bf16 v[2:17], v[90:93], v[94:97], v[2:17]
	v_mfma_f32_32x32x16_bf16 v[18:33], v[102:105], v[98:101], v[18:33]
	v_mfma_f32_32x32x16_bf16 v[2:17], v[110:113], v[98:101], v[2:17]
	v_mfma_f32_32x32x16_bf16 v[18:33], v[106:109], v[118:121], v[18:33]
	v_mfma_f32_32x32x16_bf16 v[2:17], v[114:117], v[118:121], v[2:17]
	s_nop 10
	s_barrier
	ds_write_b128 v34, v[18:21]
	ds_write_b128 v34, v[2:5] offset:128
	ds_write_b128 v34, v[22:25] offset:32
	ds_write_b128 v34, v[6:9] offset:160
	ds_write_b128 v34, v[26:29] offset:64
	ds_write_b128 v34, v[10:13] offset:192
	ds_write_b128 v34, v[30:33] offset:96
	ds_write_b128 v34, v[14:17] offset:224
	v_add_u32_e32 v2, s26, v37
	v_ashrrev_i32_e32 v13, 4, v2
	v_lshlrev_b32_e32 v2, 2, v37
	v_and_b32_e32 v20, 60, v2
	v_lshlrev_b32_e32 v12, 2, v20
	v_mul_lo_u32 v2, v13, s57
	v_add3_u32 v21, 0, v12, v2
	s_waitcnt lgkmcnt(0)
	s_barrier
	ds_read_b128 v[2:5], v21
	ds_read_b128 v[6:9], v21 offset:8704
	ds_read_b128 v[14:17], v21 offset:17408
	s_waitcnt lgkmcnt(2)
	v_pk_add_f32 v[4:5], v[4:5], 0 op_sel_hi:[1,0]
	v_pk_add_f32 v[10:11], v[2:3], 0 op_sel_hi:[1,0]
	s_waitcnt lgkmcnt(1)
	v_pk_add_f32 v[8:9], v[4:5], v[8:9]
	ds_read_b128 v[2:5], v21 offset:26112
	v_pk_add_f32 v[10:11], v[10:11], v[6:7]
	s_waitcnt lgkmcnt(1)
	v_pk_add_f32 v[16:17], v[8:9], v[16:17]
	ds_read_b128 v[6:9], v21 offset:34816
	v_pk_add_f32 v[10:11], v[10:11], v[14:15]
	s_waitcnt lgkmcnt(1)
	v_pk_add_f32 v[14:15], v[16:17], v[4:5]
	v_pk_add_f32 v[16:17], v[10:11], v[2:3]
	ds_read_b128 v[2:5], v21 offset:43520
	s_waitcnt lgkmcnt(1)
	v_pk_add_f32 v[18:19], v[14:15], v[8:9]
	ds_read_b128 v[8:11], v21 offset:52224
	v_pk_add_f32 v[6:7], v[16:17], v[6:7]
	ds_read_b128 v[14:17], v21 offset:60928
	s_waitcnt lgkmcnt(2)
	v_pk_add_f32 v[2:3], v[6:7], v[2:3]
	v_add_u32_e32 v6, s28, v13
	v_pk_add_f32 v[4:5], v[18:19], v[4:5]
	v_ashrrev_i32_e32 v7, 31, v6
	s_waitcnt lgkmcnt(1)
	v_pk_add_f32 v[4:5], v[4:5], v[10:11]
	v_pk_add_f32 v[2:3], v[2:3], v[8:9]
	v_lshlrev_b64 v[10:11], 9, v[6:7]
	s_and_b32 s28, s30, 0x1c0
	s_waitcnt lgkmcnt(0)
	v_pk_add_f32 v[4:5], v[4:5], v[16:17]
	v_pk_add_f32 v[2:3], v[2:3], v[14:15]
	v_or3_b32 v10, v10, s28, v20
	s_cmp_gt_i32 s64, 1
	s_mov_b64 s[28:29], -1
	s_barrier
	s_cbranch_scc0 .LBB0_138
	s_mov_b64 s[36:37], -1
	s_mov_b64 s[28:29], 0
	s_cmp_lt_i32 s64, 4
	s_mov_b64 s[30:31], 0
	s_mov_b64 s[34:35], 0
	s_cbranch_scc1 .LBB0_131
	s_cmp_lg_u32 s64, 4
	s_mov_b64 s[30:31], -1
	s_cselect_b64 s[34:35], -1, 0
	s_cbranch_execz .LBB0_132

.LBB0_666:
	s_mul_hi_i32 s12, s57, 0x2aaaaaab
	s_lshr_b32 s13, s12, 31
	s_ashr_i32 s12, s12, 3
	s_add_i32 s27, s12, s13
	s_mul_i32 s12, s27, 0xffffffd0
	s_add_i32 s60, s57, s12
	s_mul_i32 s12, s27, 0xfffff400
	s_add_i32 s26, s34, s12
	s_and_b32 s12, s26, 0xffffff00
	s_and_b32 s13, s36, 0x60
	s_or_b32 s12, s12, s13
	s_ashr_i32 s13, s12, 31
	s_lshl_b64 s[28:29], s[12:13], 11
	s_add_u32 s28, s3, s28
	s_addc_u32 s29, s39, s29
	s_bitset1_b32 s12, 7
	s_ashr_i32 s13, s12, 31
	v_mov_b32_e32 v37, v228
	s_lshl_b64 s[12:13], s[12:13], 11
	s_add_u32 s30, s3, s12
	v_and_b32_e32 v122, 31, v37
	v_ashrrev_i32_e32 v123, 5, v37
	s_addc_u32 s31, s39, s13
	s_lshl_b32 s12, s27, 5
	s_ashr_i32 s13, s12, 31
	s_lshl_b64 s[64:65], s[12:13], 11
	s_add_u32 s64, s58, s64
	s_addc_u32 s65, s59, s65
	s_waitcnt vmcnt(0) lgkmcnt(0)
	s_barrier
	s_mov_b32 s101, m0
	s_mul_i32 s100, s2, 0x180
	v_lshrrev_b32_e32 v14, 2, v37
	v_bfe_u32 v15, v37, 4, 2
	v_lshlrev_b32_e32 v14, 11, v14
	v_xor_b32_e32 v15, v15, v37
	v_bfe_u32 v16, v122, 2, 2
	v_and_b32_e32 v15, 3, v15
	v_xor_b32_e32 v16, v16, v123
	v_lshl_or_b32 v14, v15, 4, v14
	v_lshlrev_b32_e32 v16, 4, v16
	v_lshl_or_b32 v15, v122, 6, v16
	v_add_u32_e32 v15, s100, v15
	v_xor_b32_e32 v16, 32, v15
	s_add_u32 s98, s28, s0
	s_addc_u32 s99, s29, 0
	s_add_i32 m0, s100, 0x0
	s_nop 0
	global_load_lds_dwordx4 v14, s[98:99]
	s_add_u32 s98, s28, s0
	s_addc_u32 s99, s29, 0
	s_add_u32 s98, s98, 0x8000
	s_addc_u32 s99, s99, 0
	s_add_i32 m0, s100, 0x400
	s_nop 0
	global_load_lds_dwordx4 v14, s[98:99]
	s_add_u32 s98, s30, s0
	s_addc_u32 s99, s31, 0
	s_add_i32 m0, s100, 0x800
	s_nop 0
	global_load_lds_dwordx4 v14, s[98:99]
	s_add_u32 s98, s30, s0
	s_addc_u32 s99, s31, 0
	s_add_u32 s98, s98, 0x8000
	s_addc_u32 s99, s99, 0
	s_add_i32 m0, s100, 0xc00
	s_nop 0
	global_load_lds_dwordx4 v14, s[98:99]
	s_add_u32 s98, s64, s0
	s_addc_u32 s99, s65, 0
	s_add_u32 s98, s98, 0x2000000
	s_addc_u32 s99, s99, 0
	s_add_i32 m0, s100, 0x1000
	s_nop 0
	global_load_lds_dwordx4 v14, s[98:99]
	s_add_u32 s98, s64, s0
	s_addc_u32 s99, s65, 0
	s_add_u32 s98, s98, 0x2008000
	s_addc_u32 s99, s99, 0
	s_add_i32 m0, s100, 0x1400
	s_nop 0
	global_load_lds_dwordx4 v14, s[98:99]
	s_add_u32 s98, s28, s0
	s_addc_u32 s99, s29, 0
	s_add_u32 s98, s98, 0x40
	s_addc_u32 s99, s99, 0
	s_add_i32 m0, s100, 0x1800
	s_nop 0
	global_load_lds_dwordx4 v14, s[98:99]
	s_add_u32 s98, s28, s0
	s_addc_u32 s99, s29, 0
	s_add_u32 s98, s98, 0x8040
	s_addc_u32 s99, s99, 0
	s_add_i32 m0, s100, 0x1c00
	s_nop 0
	global_load_lds_dwordx4 v14, s[98:99]
	s_add_u32 s98, s30, s0
	s_addc_u32 s99, s31, 0
	s_add_u32 s98, s98, 0x40
	s_addc_u32 s99, s99, 0
	s_add_i32 m0, s100, 0x2000
	s_nop 0
	global_load_lds_dwordx4 v14, s[98:99]
	s_add_u32 s98, s30, s0
	s_addc_u32 s99, s31, 0
	s_add_u32 s98, s98, 0x8040
	s_addc_u32 s99, s99, 0
	s_add_i32 m0, s100, 0x2400
	s_nop 0
	global_load_lds_dwordx4 v14, s[98:99]
	s_add_u32 s98, s64, s0
	s_addc_u32 s99, s65, 0
	s_add_u32 s98, s98, 0x2000040
	s_addc_u32 s99, s99, 0
	s_add_i32 m0, s100, 0x2800
	s_nop 0
	global_load_lds_dwordx4 v14, s[98:99]
	s_add_u32 s98, s64, s0
	s_addc_u32 s99, s65, 0
	s_add_u32 s98, s98, 0x2008040
	s_addc_u32 s99, s99, 0
	s_add_i32 m0, s100, 0x2c00
	s_nop 0
	global_load_lds_dwordx4 v14, s[98:99]
	s_waitcnt vmcnt(6)
	ds_read_b128 v[2:5], v15
	ds_read_b128 v[6:9], v15 offset:2048
	ds_read_b128 v[10:13], v15 offset:4096
	ds_read_b128 v[38:41], v16
	ds_read_b128 v[42:45], v16 offset:2048
	ds_read_b128 v[46:49], v16 offset:4096
	s_waitcnt lgkmcnt(0)
	s_add_u32 s98, s28, s0
	s_addc_u32 s99, s29, 0
	s_add_u32 s98, s98, 0x80
	s_addc_u32 s99, s99, 0
	s_add_i32 m0, s100, 0x0
	s_nop 0
	global_load_lds_dwordx4 v14, s[98:99]
	s_add_u32 s98, s28, s0
	s_addc_u32 s99, s29, 0
	s_add_u32 s98, s98, 0x8080
	s_addc_u32 s99, s99, 0
	s_add_i32 m0, s100, 0x400
	s_nop 0
	global_load_lds_dwordx4 v14, s[98:99]
	s_add_u32 s98, s30, s0
	s_addc_u32 s99, s31, 0
	s_add_u32 s98, s98, 0x80
	s_addc_u32 s99, s99, 0
	s_add_i32 m0, s100, 0x800
	s_nop 0
	global_load_lds_dwordx4 v14, s[98:99]
	s_add_u32 s98, s30, s0
	s_addc_u32 s99, s31, 0
	s_add_u32 s98, s98, 0x8080
	s_addc_u32 s99, s99, 0
	s_add_i32 m0, s100, 0xc00
	s_nop 0
	global_load_lds_dwordx4 v14, s[98:99]
	s_add_u32 s98, s64, s0
	s_addc_u32 s99, s65, 0
	s_add_u32 s98, s98, 0x2000080
	s_addc_u32 s99, s99, 0
	s_add_i32 m0, s100, 0x1000
	s_nop 0
	global_load_lds_dwordx4 v14, s[98:99]
	s_add_u32 s98, s64, s0
	s_addc_u32 s99, s65, 0
	s_add_u32 s98, s98, 0x2008080
	s_addc_u32 s99, s99, 0
	s_add_i32 m0, s100, 0x1400
	s_nop 0
	global_load_lds_dwordx4 v14, s[98:99]
	s_waitcnt vmcnt(6)
	ds_read_b128 v[54:57], v15 offset:6144
	ds_read_b128 v[62:65], v15 offset:8192
	ds_read_b128 v[50:53], v15 offset:10240
	ds_read_b128 v[58:61], v16 offset:6144
	ds_read_b128 v[66:69], v16 offset:8192
	ds_read_b128 v[70:73], v16 offset:10240
	s_waitcnt lgkmcnt(0)
	s_add_u32 s98, s28, s0
	s_addc_u32 s99, s29, 0
	s_add_u32 s98, s98, 0xc0
	s_addc_u32 s99, s99, 0
	s_add_i32 m0, s100, 0x1800
	s_nop 0
	global_load_lds_dwordx4 v14, s[98:99]
	s_add_u32 s98, s28, s0
	s_addc_u32 s99, s29, 0
	s_add_u32 s98, s98, 0x80c0
	s_addc_u32 s99, s99, 0
	s_add_i32 m0, s100, 0x1c00
	s_nop 0
	global_load_lds_dwordx4 v14, s[98:99]
	s_add_u32 s98, s30, s0
	s_addc_u32 s99, s31, 0
	s_add_u32 s98, s98, 0xc0
	s_addc_u32 s99, s99, 0
	s_add_i32 m0, s100, 0x2000
	s_nop 0
	global_load_lds_dwordx4 v14, s[98:99]
	s_add_u32 s98, s30, s0
	s_addc_u32 s99, s31, 0
	s_add_u32 s98, s98, 0x80c0
	s_addc_u32 s99, s99, 0
	s_add_i32 m0, s100, 0x2400
	s_nop 0
	global_load_lds_dwordx4 v14, s[98:99]
	s_add_u32 s98, s64, s0
	s_addc_u32 s99, s65, 0
	s_add_u32 s98, s98, 0x20000c0
	s_addc_u32 s99, s99, 0
	s_add_i32 m0, s100, 0x2800
	s_nop 0
	global_load_lds_dwordx4 v14, s[98:99]
	s_add_u32 s98, s64, s0
	s_addc_u32 s99, s65, 0
	s_add_u32 s98, s98, 0x20080c0
	s_addc_u32 s99, s99, 0
	s_add_i32 m0, s100, 0x2c00
	s_nop 0
	global_load_lds_dwordx4 v14, s[98:99]
	s_waitcnt vmcnt(6)
	ds_read_b128 v[78:81], v15
	ds_read_b128 v[86:89], v15 offset:2048
	ds_read_b128 v[74:77], v15 offset:4096
	ds_read_b128 v[82:85], v16
	ds_read_b128 v[90:93], v16 offset:2048
	ds_read_b128 v[94:97], v16 offset:4096
	s_waitcnt vmcnt(0)
	ds_read_b128 v[102:105], v15 offset:6144
	ds_read_b128 v[110:113], v15 offset:8192
	ds_read_b128 v[98:101], v15 offset:10240
	ds_read_b128 v[106:109], v16 offset:6144
	ds_read_b128 v[114:117], v16 offset:8192
	ds_read_b128 v[118:121], v16 offset:10240
	s_mov_b32 m0, s101
	s_waitcnt lgkmcnt(0)
	v_mfma_f32_32x32x16_bf16 v[18:33], v[2:5], v[10:13], 0
	v_or_b32_e32 v34, s2, v122
	v_mul_lo_u32 v34, v34, s55
	s_ashr_i32 s61, s60, 3
	v_mfma_f32_32x32x16_bf16 v[2:17], v[6:9], v[10:13], 0
	v_mfma_f32_32x32x16_bf16 v[18:33], v[38:41], v[46:49], v[18:33]
	v_lshlrev_b32_e32 v38, 4, v123
	v_add3_u32 v34, 0, v34, v38
	v_mfma_f32_32x32x16_bf16 v[2:17], v[42:45], v[46:49], v[2:17]
	v_mfma_f32_32x32x16_bf16 v[18:33], v[54:57], v[50:53], v[18:33]
	v_mfma_f32_32x32x16_bf16 v[2:17], v[62:65], v[50:53], v[2:17]
	v_mfma_f32_32x32x16_bf16 v[18:33], v[58:61], v[70:73], v[18:33]
	v_mfma_f32_32x32x16_bf16 v[2:17], v[66:69], v[70:73], v[2:17]
	v_mfma_f32_32x32x16_bf16 v[18:33], v[78:81], v[74:77], v[18:33]
	v_mfma_f32_32x32x16_bf16 v[2:17], v[86:89], v[74:77], v[2:17]
	v_mfma_f32_32x32x16_bf16 v[18:33], v[82:85], v[94:97], v[18:33]
	v_mfma_f32_32x32x16_bf16 v[2:17], v[90:93], v[94:97], v[2:17]
	v_mfma_f32_32x32x16_bf16 v[18:33], v[102:105], v[98:101], v[18:33]
	v_mfma_f32_32x32x16_bf16 v[2:17], v[110:113], v[98:101], v[2:17]
	v_mfma_f32_32x32x16_bf16 v[18:33], v[106:109], v[118:121], v[18:33]
	v_mfma_f32_32x32x16_bf16 v[2:17], v[114:117], v[118:121], v[2:17]
	s_nop 10
	s_barrier
	ds_write_b128 v34, v[18:21]
	ds_write_b128 v34, v[2:5] offset:128
	ds_write_b128 v34, v[22:25] offset:32
	ds_write_b128 v34, v[6:9] offset:160
	ds_write_b128 v34, v[26:29] offset:64
	ds_write_b128 v34, v[10:13] offset:192
	ds_write_b128 v34, v[30:33] offset:96
	ds_write_b128 v34, v[14:17] offset:224
	v_add_u32_e32 v2, s33, v37
	v_ashrrev_i32_e32 v13, 4, v2
	v_lshlrev_b32_e32 v2, 2, v37
	v_and_b32_e32 v20, 60, v2
	v_lshlrev_b32_e32 v12, 2, v20
	v_mul_lo_u32 v2, v13, s55
	v_add3_u32 v21, 0, v12, v2
	s_waitcnt lgkmcnt(0)
	s_barrier
	ds_read_b128 v[2:5], v21
	ds_read_b128 v[6:9], v21 offset:8704
	ds_read_b128 v[14:17], v21 offset:17408
	s_waitcnt lgkmcnt(2)
	v_pk_add_f32 v[4:5], v[4:5], 0 op_sel_hi:[1,0]
	v_pk_add_f32 v[10:11], v[2:3], 0 op_sel_hi:[1,0]
	s_waitcnt lgkmcnt(1)
	v_pk_add_f32 v[8:9], v[4:5], v[8:9]
	ds_read_b128 v[2:5], v21 offset:26112
	v_pk_add_f32 v[10:11], v[10:11], v[6:7]
	s_waitcnt lgkmcnt(1)
	v_pk_add_f32 v[16:17], v[8:9], v[16:17]
	ds_read_b128 v[6:9], v21 offset:34816
	v_pk_add_f32 v[10:11], v[10:11], v[14:15]
	s_waitcnt lgkmcnt(1)
	v_pk_add_f32 v[14:15], v[16:17], v[4:5]
	v_pk_add_f32 v[16:17], v[10:11], v[2:3]
	ds_read_b128 v[2:5], v21 offset:43520
	s_waitcnt lgkmcnt(1)
	v_pk_add_f32 v[18:19], v[14:15], v[8:9]
	ds_read_b128 v[8:11], v21 offset:52224
	v_pk_add_f32 v[6:7], v[16:17], v[6:7]
	ds_read_b128 v[14:17], v21 offset:60928
	s_waitcnt lgkmcnt(2)
	v_pk_add_f32 v[2:3], v[6:7], v[2:3]
	v_add_u32_e32 v6, s12, v13
	v_pk_add_f32 v[4:5], v[18:19], v[4:5]
	v_ashrrev_i32_e32 v7, 31, v6
	s_waitcnt lgkmcnt(1)
	v_pk_add_f32 v[4:5], v[4:5], v[10:11]
	v_pk_add_f32 v[2:3], v[2:3], v[8:9]
	v_lshlrev_b64 v[10:11], 9, v[6:7]
	s_and_b32 s12, s26, 0x1c0
	s_waitcnt lgkmcnt(0)
	v_pk_add_f32 v[4:5], v[4:5], v[16:17]
	v_pk_add_f32 v[2:3], v[2:3], v[14:15]
	v_or3_b32 v10, v10, s12, v20
	s_cmp_gt_i32 s61, 1
	s_mov_b64 s[12:13], -1
	s_barrier
	s_cbranch_scc0 .LBB0_679
	s_mov_b64 s[30:31], -1
	s_mov_b64 s[12:13], 0
	s_cmp_lt_i32 s61, 4
	s_mov_b64 s[26:27], 0
	s_mov_b64 s[28:29], 0
	s_cbranch_scc1 .LBB0_672
	s_cmp_lg_u32 s61, 4
	s_mov_b64 s[26:27], -1
	s_cselect_b64 s[28:29], -1, 0
	s_cbranch_execz .LBB0_673

.LBB0_1165:
	s_and_b32 s30, s25, 7
	s_lshl_b32 s18, s30, 16
	s_add_u32 s26, s44, s18
	v_mov_b32_e32 v1, v228
	s_addc_u32 s27, s45, 0
	s_and_b32 s18, s21, 0xffffffe0
	s_ashr_i32 s19, s18, 31
	v_and_b32_e32 v72, 31, v1
	v_ashrrev_i32_e32 v73, 5, v1
	s_lshl_b64 s[28:29], s[18:19], 10
	s_add_u32 s28, s8, s28
	s_addc_u32 s29, s9, s29
	s_waitcnt vmcnt(0) lgkmcnt(0)
	s_barrier
	s_mov_b32 s101, m0
	s_mul_i32 s100, s20, 0x180
	v_lshrrev_b32_e32 v24, 2, v1
	v_bfe_u32 v25, v1, 4, 2
	v_lshlrev_b32_e32 v24, 10, v24
	v_xor_b32_e32 v25, v25, v1
	v_bfe_u32 v26, v72, 2, 2
	v_and_b32_e32 v25, 3, v25
	v_xor_b32_e32 v26, v26, v73
	v_lshl_or_b32 v24, v25, 4, v24
	v_lshlrev_b32_e32 v26, 4, v26
	v_lshl_or_b32 v25, v72, 6, v26
	v_add_u32_e32 v25, s100, v25
	v_xor_b32_e32 v26, 32, v25
	s_add_u32 s98, s26, s4
	s_addc_u32 s99, s27, 0
	s_add_i32 m0, s100, 0x0
	s_nop 0
	global_load_lds_dwordx4 v24, s[98:99]
	s_add_u32 s98, s26, s4
	s_addc_u32 s99, s27, 0
	s_add_u32 s98, s98, 0x4000
	s_addc_u32 s99, s99, 0
	s_add_i32 m0, s100, 0x400
	s_nop 0
	global_load_lds_dwordx4 v24, s[98:99]
	s_add_u32 s98, s26, s4
	s_addc_u32 s99, s27, 0
	s_add_u32 s98, s98, 0x8000
	s_addc_u32 s99, s99, 0
	s_add_i32 m0, s100, 0x800
	s_nop 0
	global_load_lds_dwordx4 v24, s[98:99]
	s_add_u32 s98, s26, s4
	s_addc_u32 s99, s27, 0
	s_add_u32 s98, s98, 0xc000
	s_addc_u32 s99, s99, 0
	s_add_i32 m0, s100, 0xc00
	s_nop 0
	global_load_lds_dwordx4 v24, s[98:99]
	s_add_u32 s98, s28, s4
	s_addc_u32 s99, s29, 0
	s_add_u32 s98, s98, 0x1000000
	s_addc_u32 s99, s99, 0
	s_add_i32 m0, s100, 0x1000
	s_nop 0
	global_load_lds_dwordx4 v24, s[98:99]
	s_add_u32 s98, s28, s4
	s_addc_u32 s99, s29, 0
	s_add_u32 s98, s98, 0x1004000
	s_addc_u32 s99, s99, 0
	s_add_i32 m0, s100, 0x1400
	s_nop 0
	global_load_lds_dwordx4 v24, s[98:99]
	s_add_u32 s98, s26, s4
	s_addc_u32 s99, s27, 0
	s_add_u32 s98, s98, 0x40
	s_addc_u32 s99, s99, 0
	s_add_i32 m0, s100, 0x1800
	s_nop 0
	global_load_lds_dwordx4 v24, s[98:99]
	s_add_u32 s98, s26, s4
	s_addc_u32 s99, s27, 0
	s_add_u32 s98, s98, 0x4040
	s_addc_u32 s99, s99, 0
	s_add_i32 m0, s100, 0x1c00
	s_nop 0
	global_load_lds_dwordx4 v24, s[98:99]
	s_add_u32 s98, s26, s4
	s_addc_u32 s99, s27, 0
	s_add_u32 s98, s98, 0x8040
	s_addc_u32 s99, s99, 0
	s_add_i32 m0, s100, 0x2000
	s_nop 0
	global_load_lds_dwordx4 v24, s[98:99]
	s_add_u32 s98, s26, s4
	s_addc_u32 s99, s27, 0
	s_add_u32 s98, s98, 0xc040
	s_addc_u32 s99, s99, 0
	s_add_i32 m0, s100, 0x2400
	s_nop 0
	global_load_lds_dwordx4 v24, s[98:99]
	s_add_u32 s98, s28, s4
	s_addc_u32 s99, s29, 0
	s_add_u32 s98, s98, 0x1000040
	s_addc_u32 s99, s99, 0
	s_add_i32 m0, s100, 0x2800
	s_nop 0
	global_load_lds_dwordx4 v24, s[98:99]
	s_add_u32 s98, s28, s4
	s_addc_u32 s99, s29, 0
	s_add_u32 s98, s98, 0x1004040
	s_addc_u32 s99, s99, 0
	s_add_i32 m0, s100, 0x2c00
	s_nop 0
	global_load_lds_dwordx4 v24, s[98:99]
	s_waitcnt vmcnt(6)
	ds_read_b128 v[10:13], v25
	ds_read_b128 v[2:5], v25 offset:2048
	ds_read_b128 v[6:9], v25 offset:4096
	ds_read_b128 v[36:39], v26
	ds_read_b128 v[40:43], v26 offset:2048
	ds_read_b128 v[56:59], v26 offset:4096
	s_waitcnt vmcnt(0)
	ds_read_b128 v[48:51], v25 offset:6144
	ds_read_b128 v[44:47], v25 offset:8192
	ds_read_b128 v[64:67], v25 offset:10240
	ds_read_b128 v[52:55], v26 offset:6144
	ds_read_b128 v[60:63], v26 offset:8192
	ds_read_b128 v[68:71], v26 offset:10240
	s_mov_b32 m0, s101
	s_waitcnt lgkmcnt(0)
	v_mfma_f32_32x32x16_bf16 v[18:33], v[10:13], v[6:9], 0
	v_or_b32_e32 v34, s20, v72
	v_mul_lo_u32 v34, v34, s24
	s_add_u32 s18, s18, 0x4000
	s_addc_u32 s19, s19, 0
	s_add_i32 s25, s25, s46
	s_add_i32 s21, s21, s22
	s_cmpk_lt_i32 s25, 0x80
	v_mfma_f32_32x32x16_bf16 v[2:17], v[2:5], v[6:9], 0
	v_mfma_f32_32x32x16_bf16 v[18:33], v[36:39], v[56:59], v[18:33]
	v_lshlrev_b32_e32 v36, 4, v73
	v_add3_u32 v34, 0, v34, v36
	v_mfma_f32_32x32x16_bf16 v[2:17], v[40:43], v[56:59], v[2:17]
	v_mfma_f32_32x32x16_bf16 v[18:33], v[48:51], v[64:67], v[18:33]
	v_mfma_f32_32x32x16_bf16 v[2:17], v[44:47], v[64:67], v[2:17]
	v_mfma_f32_32x32x16_bf16 v[18:33], v[52:55], v[68:71], v[18:33]
	v_mfma_f32_32x32x16_bf16 v[2:17], v[60:63], v[68:71], v[2:17]
	s_nop 10
	s_barrier
	ds_write_b128 v34, v[18:21]
	ds_write_b128 v34, v[2:5] offset:128
	ds_write_b128 v34, v[22:25] offset:32
	ds_write_b128 v34, v[6:9] offset:160
	ds_write_b128 v34, v[26:29] offset:64
	ds_write_b128 v34, v[10:13] offset:192
	ds_write_b128 v34, v[30:33] offset:96
	ds_write_b128 v34, v[14:17] offset:224
	v_add_u32_e32 v2, s0, v1
	v_lshlrev_b32_e32 v1, 2, v1
	v_ashrrev_i32_e32 v36, 4, v2
	v_and_b32_e32 v1, 60, v1
	v_lshlrev_b32_e32 v2, 2, v1
	v_mul_lo_u32 v3, v36, s24
	v_lshl_or_b32 v1, s30, 6, v1
	v_add3_u32 v30, 0, v2, v3
	v_ashrrev_i32_e32 v37, 31, v36
	v_lshlrev_b32_e32 v34, 2, v1
	s_waitcnt lgkmcnt(0)
	s_barrier
	ds_read_b128 v[2:5], v30
	ds_read_b128 v[6:9], v30 offset:8704
	ds_read_b128 v[10:13], v30 offset:17408
	ds_read_b128 v[14:17], v30 offset:26112
	ds_read_b128 v[18:21], v30 offset:34816
	ds_read_b128 v[22:25], v30 offset:43520
	ds_read_b128 v[26:29], v30 offset:52224
	ds_read_b128 v[30:33], v30 offset:60928
	s_waitcnt lgkmcnt(0)
	s_barrier
	v_lshl_add_u64 v[40:41], s[18:19], 0, v[36:37]
	global_load_dwordx4 v[36:39], v34, s[56:57]
	v_lshlrev_b64 v[42:43], 10, v[40:41]
	v_lshl_add_u64 v[44:45], s[8:9], 0, v[42:43]
	v_lshlrev_b32_e32 v34, 1, v1
	v_lshl_add_u64 v[44:45], v[44:45], 0, v[34:35]
	v_lshl_add_u64 v[42:43], s[6:7], 0, v[42:43]
	global_load_dwordx2 v[44:45], v[44:45], off
	v_lshl_add_u64 v[42:43], v[42:43], 0, v[34:35]
	global_load_dwordx2 v[42:43], v[42:43], off
	v_pk_add_f32 v[4:5], v[4:5], 0 op_sel_hi:[1,0]
	v_pk_add_f32 v[2:3], v[2:3], 0 op_sel_hi:[1,0]
	v_pk_add_f32 v[4:5], v[4:5], v[8:9]
	v_pk_add_f32 v[2:3], v[2:3], v[6:7]
	v_pk_add_f32 v[4:5], v[4:5], v[12:13]
	v_pk_add_f32 v[2:3], v[2:3], v[10:11]
	v_pk_add_f32 v[4:5], v[4:5], v[16:17]
	v_pk_add_f32 v[2:3], v[2:3], v[14:15]
	v_pk_add_f32 v[4:5], v[4:5], v[20:21]
	v_pk_add_f32 v[2:3], v[2:3], v[18:19]
	v_pk_add_f32 v[4:5], v[4:5], v[24:25]
	v_pk_add_f32 v[2:3], v[2:3], v[22:23]
	v_pk_add_f32 v[4:5], v[4:5], v[28:29]
	v_pk_add_f32 v[2:3], v[2:3], v[26:27]
	v_pk_add_f32 v[4:5], v[4:5], v[32:33]
	v_pk_add_f32 v[2:3], v[2:3], v[30:31]
	v_lshlrev_b64 v[40:41], 11, v[40:41]
	v_lshl_add_u64 v[40:41], s[10:11], 0, v[40:41]
	v_lshl_add_u64 v[40:41], v[40:41], 0, v[34:35]
	s_waitcnt vmcnt(2)
	v_add_f32_e32 v2, v2, v36
	v_add_f32_e32 v3, v3, v37
	v_add_f32_e32 v4, v4, v38
	v_add_f32_e32 v5, v5, v39
	v_mul_f32_e32 v2, 0xbfb8aa3b, v2
	v_mul_f32_e32 v3, 0xbfb8aa3b, v3
	v_mul_f32_e32 v4, 0xbfb8aa3b, v4
	v_mul_f32_e32 v5, 0xbfb8aa3b, v5
	v_exp_f32_e32 v2, v2
	v_exp_f32_e32 v3, v3
	v_exp_f32_e32 v4, v4
	v_exp_f32_e32 v5, v5
	v_add_f32_e32 v2, 1.0, v2
	v_add_f32_e32 v3, 1.0, v3
	v_add_f32_e32 v4, 1.0, v4
	v_add_f32_e32 v5, 1.0, v5
	v_rcp_f32_e32 v2, v2
	v_rcp_f32_e32 v3, v3
	v_rcp_f32_e32 v4, v4
	v_rcp_f32_e32 v5, v5
	s_waitcnt vmcnt(1)
	v_lshlrev_b32_e32 v1, 16, v44
	v_and_b32_e32 v7, 0xffff0000, v44
	v_lshlrev_b32_e32 v9, 16, v45
	s_waitcnt vmcnt(0)
	v_and_b32_e32 v8, 0xffff0000, v42
	v_lshlrev_b32_e32 v10, 16, v43
	v_and_b32_e32 v11, 0xffff0000, v45
	v_mul_f32_e32 v1, v2, v1
	v_mul_f32_e32 v2, v3, v7
	v_mul_f32_e32 v3, v4, v9
	v_lshlrev_b32_e32 v6, 16, v42
	v_and_b32_e32 v12, 0xffff0000, v43
	v_mul_f32_e32 v4, v5, v11
	v_mul_f32_e32 v2, v2, v8
	v_mul_f32_e32 v3, v3, v10
	v_mul_f32_e32 v1, v1, v6
	v_mul_f32_e32 v4, v4, v12
	v_cvt_pk_bf16_f32 v2, v1, v2
	v_cvt_pk_bf16_f32 v3, v3, v4
	global_store_dwordx2 v[40:41], v[2:3], off offset:1024
	s_cbranch_scc1 .LBB0_1165

.LBB0_1187:
	s_and_b32 s23, s2, 7
	s_lshl_b32 s16, s23, 16
	s_add_u32 s24, s44, s16
	v_mov_b32_e32 v1, v228
	s_addc_u32 s25, s45, 0
	s_and_b32 s16, s19, 0xffffffe0
	s_ashr_i32 s17, s16, 31
	v_and_b32_e32 v72, 31, v1
	v_ashrrev_i32_e32 v73, 5, v1
	s_lshl_b64 s[26:27], s[16:17], 10
	s_add_u32 s26, s8, s26
	s_addc_u32 s27, s9, s27
	s_waitcnt vmcnt(0) lgkmcnt(0)
	s_barrier
	s_mov_b32 s101, m0
	s_mul_i32 s100, s18, 0x180
	v_lshrrev_b32_e32 v24, 2, v1
	v_bfe_u32 v25, v1, 4, 2
	v_lshlrev_b32_e32 v24, 10, v24
	v_xor_b32_e32 v25, v25, v1
	v_bfe_u32 v26, v72, 2, 2
	v_and_b32_e32 v25, 3, v25
	v_xor_b32_e32 v26, v26, v73
	v_lshl_or_b32 v24, v25, 4, v24
	v_lshlrev_b32_e32 v26, 4, v26
	v_lshl_or_b32 v25, v72, 6, v26
	v_add_u32_e32 v25, s100, v25
	v_xor_b32_e32 v26, 32, v25
	s_add_u32 s98, s24, s4
	s_addc_u32 s99, s25, 0
	s_add_i32 m0, s100, 0x0
	s_nop 0
	global_load_lds_dwordx4 v24, s[98:99]
	s_add_u32 s98, s24, s4
	s_addc_u32 s99, s25, 0
	s_add_u32 s98, s98, 0x4000
	s_addc_u32 s99, s99, 0
	s_add_i32 m0, s100, 0x400
	s_nop 0
	global_load_lds_dwordx4 v24, s[98:99]
	s_add_u32 s98, s24, s4
	s_addc_u32 s99, s25, 0
	s_add_u32 s98, s98, 0x8000
	s_addc_u32 s99, s99, 0
	s_add_i32 m0, s100, 0x800
	s_nop 0
	global_load_lds_dwordx4 v24, s[98:99]
	s_add_u32 s98, s24, s4
	s_addc_u32 s99, s25, 0
	s_add_u32 s98, s98, 0xc000
	s_addc_u32 s99, s99, 0
	s_add_i32 m0, s100, 0xc00
	s_nop 0
	global_load_lds_dwordx4 v24, s[98:99]
	s_add_u32 s98, s26, s4
	s_addc_u32 s99, s27, 0
	s_add_u32 s98, s98, 0x1000000
	s_addc_u32 s99, s99, 0
	s_add_i32 m0, s100, 0x1000
	s_nop 0
	global_load_lds_dwordx4 v24, s[98:99]
	s_add_u32 s98, s26, s4
	s_addc_u32 s99, s27, 0
	s_add_u32 s98, s98, 0x1004000
	s_addc_u32 s99, s99, 0
	s_add_i32 m0, s100, 0x1400
	s_nop 0
	global_load_lds_dwordx4 v24, s[98:99]
	s_add_u32 s98, s24, s4
	s_addc_u32 s99, s25, 0
	s_add_u32 s98, s98, 0x40
	s_addc_u32 s99, s99, 0
	s_add_i32 m0, s100, 0x1800
	s_nop 0
	global_load_lds_dwordx4 v24, s[98:99]
	s_add_u32 s98, s24, s4
	s_addc_u32 s99, s25, 0
	s_add_u32 s98, s98, 0x4040
	s_addc_u32 s99, s99, 0
	s_add_i32 m0, s100, 0x1c00
	s_nop 0
	global_load_lds_dwordx4 v24, s[98:99]
	s_add_u32 s98, s24, s4
	s_addc_u32 s99, s25, 0
	s_add_u32 s98, s98, 0x8040
	s_addc_u32 s99, s99, 0
	s_add_i32 m0, s100, 0x2000
	s_nop 0
	global_load_lds_dwordx4 v24, s[98:99]
	s_add_u32 s98, s24, s4
	s_addc_u32 s99, s25, 0
	s_add_u32 s98, s98, 0xc040
	s_addc_u32 s99, s99, 0
	s_add_i32 m0, s100, 0x2400
	s_nop 0
	global_load_lds_dwordx4 v24, s[98:99]
	s_add_u32 s98, s26, s4
	s_addc_u32 s99, s27, 0
	s_add_u32 s98, s98, 0x1000040
	s_addc_u32 s99, s99, 0
	s_add_i32 m0, s100, 0x2800
	s_nop 0
	global_load_lds_dwordx4 v24, s[98:99]
	s_add_u32 s98, s26, s4
	s_addc_u32 s99, s27, 0
	s_add_u32 s98, s98, 0x1004040
	s_addc_u32 s99, s99, 0
	s_add_i32 m0, s100, 0x2c00
	s_nop 0
	global_load_lds_dwordx4 v24, s[98:99]
	s_waitcnt vmcnt(6)
	ds_read_b128 v[10:13], v25
	ds_read_b128 v[2:5], v25 offset:2048
	ds_read_b128 v[6:9], v25 offset:4096
	ds_read_b128 v[36:39], v26
	ds_read_b128 v[40:43], v26 offset:2048
	ds_read_b128 v[56:59], v26 offset:4096
	s_waitcnt vmcnt(0)
	ds_read_b128 v[48:51], v25 offset:6144
	ds_read_b128 v[44:47], v25 offset:8192
	ds_read_b128 v[64:67], v25 offset:10240
	ds_read_b128 v[52:55], v26 offset:6144
	ds_read_b128 v[60:63], v26 offset:8192
	ds_read_b128 v[68:71], v26 offset:10240
	s_mov_b32 m0, s101
	s_waitcnt lgkmcnt(0)
	v_mfma_f32_32x32x16_bf16 v[18:33], v[10:13], v[6:9], 0
	v_or_b32_e32 v34, s18, v72
	v_mul_lo_u32 v34, v34, s22
	s_add_u32 s16, s16, 0x4000
	s_addc_u32 s17, s17, 0
	s_add_i32 s2, s2, s46
	s_add_i32 s19, s19, s20
	s_cmpk_lt_i32 s2, 0x80
	v_mfma_f32_32x32x16_bf16 v[2:17], v[2:5], v[6:9], 0
	v_mfma_f32_32x32x16_bf16 v[18:33], v[36:39], v[56:59], v[18:33]
	v_lshlrev_b32_e32 v36, 4, v73
	v_add3_u32 v34, 0, v34, v36
	v_mfma_f32_32x32x16_bf16 v[2:17], v[40:43], v[56:59], v[2:17]
	v_mfma_f32_32x32x16_bf16 v[18:33], v[48:51], v[64:67], v[18:33]
	v_mfma_f32_32x32x16_bf16 v[2:17], v[44:47], v[64:67], v[2:17]
	v_mfma_f32_32x32x16_bf16 v[18:33], v[52:55], v[68:71], v[18:33]
	v_mfma_f32_32x32x16_bf16 v[2:17], v[60:63], v[68:71], v[2:17]
	s_nop 10
	s_barrier
	ds_write_b128 v34, v[18:21]
	ds_write_b128 v34, v[2:5] offset:128
	ds_write_b128 v34, v[22:25] offset:32
	ds_write_b128 v34, v[6:9] offset:160
	ds_write_b128 v34, v[26:29] offset:64
	ds_write_b128 v34, v[10:13] offset:192
	ds_write_b128 v34, v[30:33] offset:96
	ds_write_b128 v34, v[14:17] offset:224
	v_add_u32_e32 v2, s0, v1
	v_lshlrev_b32_e32 v1, 2, v1
	v_ashrrev_i32_e32 v36, 4, v2
	v_and_b32_e32 v1, 60, v1
	v_lshlrev_b32_e32 v2, 2, v1
	v_mul_lo_u32 v3, v36, s22
	v_lshl_or_b32 v1, s23, 6, v1
	v_add3_u32 v30, 0, v2, v3
	v_ashrrev_i32_e32 v37, 31, v36
	v_lshlrev_b32_e32 v34, 2, v1
	s_waitcnt lgkmcnt(0)
	s_barrier
	ds_read_b128 v[2:5], v30
	ds_read_b128 v[6:9], v30 offset:8704
	ds_read_b128 v[10:13], v30 offset:17408
	ds_read_b128 v[14:17], v30 offset:26112
	ds_read_b128 v[18:21], v30 offset:34816
	ds_read_b128 v[22:25], v30 offset:43520
	ds_read_b128 v[26:29], v30 offset:52224
	ds_read_b128 v[30:33], v30 offset:60928
	s_waitcnt lgkmcnt(0)
	s_barrier
	v_lshl_add_u64 v[40:41], s[16:17], 0, v[36:37]
	global_load_dwordx4 v[36:39], v34, s[56:57]
	v_lshlrev_b64 v[42:43], 10, v[40:41]
	v_lshl_add_u64 v[44:45], s[8:9], 0, v[42:43]
	v_lshlrev_b32_e32 v34, 1, v1
	v_lshl_add_u64 v[44:45], v[44:45], 0, v[34:35]
	v_lshl_add_u64 v[42:43], s[6:7], 0, v[42:43]
	global_load_dwordx2 v[44:45], v[44:45], off
	v_lshl_add_u64 v[42:43], v[42:43], 0, v[34:35]
	global_load_dwordx2 v[42:43], v[42:43], off
	v_pk_add_f32 v[4:5], v[4:5], 0 op_sel_hi:[1,0]
	v_pk_add_f32 v[2:3], v[2:3], 0 op_sel_hi:[1,0]
	v_pk_add_f32 v[4:5], v[4:5], v[8:9]
	v_pk_add_f32 v[2:3], v[2:3], v[6:7]
	v_pk_add_f32 v[4:5], v[4:5], v[12:13]
	v_pk_add_f32 v[2:3], v[2:3], v[10:11]
	v_pk_add_f32 v[4:5], v[4:5], v[16:17]
	v_pk_add_f32 v[2:3], v[2:3], v[14:15]
	v_pk_add_f32 v[4:5], v[4:5], v[20:21]
	v_pk_add_f32 v[2:3], v[2:3], v[18:19]
	v_pk_add_f32 v[4:5], v[4:5], v[24:25]
	v_pk_add_f32 v[2:3], v[2:3], v[22:23]
	v_pk_add_f32 v[4:5], v[4:5], v[28:29]
	v_pk_add_f32 v[2:3], v[2:3], v[26:27]
	v_pk_add_f32 v[4:5], v[4:5], v[32:33]
	v_pk_add_f32 v[2:3], v[2:3], v[30:31]
	v_lshlrev_b64 v[40:41], 11, v[40:41]
	v_lshl_add_u64 v[40:41], s[10:11], 0, v[40:41]
	v_lshl_add_u64 v[40:41], v[40:41], 0, v[34:35]
	s_waitcnt vmcnt(2)
	v_add_f32_e32 v2, v2, v36
	v_add_f32_e32 v3, v3, v37
	v_add_f32_e32 v4, v4, v38
	v_add_f32_e32 v5, v5, v39
	v_mul_f32_e32 v2, 0xbfb8aa3b, v2
	v_mul_f32_e32 v3, 0xbfb8aa3b, v3
	v_mul_f32_e32 v4, 0xbfb8aa3b, v4
	v_mul_f32_e32 v5, 0xbfb8aa3b, v5
	v_exp_f32_e32 v2, v2
	v_exp_f32_e32 v3, v3
	v_exp_f32_e32 v4, v4
	v_exp_f32_e32 v5, v5
	v_add_f32_e32 v2, 1.0, v2
	v_add_f32_e32 v3, 1.0, v3
	v_add_f32_e32 v4, 1.0, v4
	v_add_f32_e32 v5, 1.0, v5
	v_rcp_f32_e32 v2, v2
	v_rcp_f32_e32 v3, v3
	v_rcp_f32_e32 v4, v4
	v_rcp_f32_e32 v5, v5
	s_waitcnt vmcnt(1)
	v_lshlrev_b32_e32 v1, 16, v44
	v_and_b32_e32 v7, 0xffff0000, v44
	v_lshlrev_b32_e32 v9, 16, v45
	s_waitcnt vmcnt(0)
	v_and_b32_e32 v8, 0xffff0000, v42
	v_lshlrev_b32_e32 v10, 16, v43
	v_and_b32_e32 v11, 0xffff0000, v45
	v_mul_f32_e32 v1, v2, v1
	v_mul_f32_e32 v2, v3, v7
	v_mul_f32_e32 v3, v4, v9
	v_lshlrev_b32_e32 v6, 16, v42
	v_and_b32_e32 v12, 0xffff0000, v43
	v_mul_f32_e32 v4, v5, v11
	v_mul_f32_e32 v2, v2, v8
	v_mul_f32_e32 v3, v3, v10
	v_mul_f32_e32 v1, v1, v6
	v_mul_f32_e32 v4, v4, v12
	v_cvt_pk_bf16_f32 v2, v1, v2
	v_cvt_pk_bf16_f32 v3, v3, v4
	global_store_dwordx2 v[40:41], v[2:3], off offset:1024
	s_cbranch_scc1 .LBB0_1187

.LBB0_1244:
	s_and_b32 s19, s18, 15
	s_ashr_i32 s12, s18, 4
	s_lshl_b32 s13, s19, 17
	s_add_u32 s20, s44, s13
	v_mov_b32_e32 v1, v228
	s_addc_u32 s21, s45, 0
	s_lshl_b32 s22, s12, 5
	s_ashr_i32 s23, s22, 31
	v_and_b32_e32 v120, 31, v1
	v_ashrrev_i32_e32 v121, 5, v1
	s_lshl_b64 s[22:23], s[22:23], 11
	s_add_u32 s22, s46, s22
	s_addc_u32 s23, s47, s23
	s_waitcnt vmcnt(0) lgkmcnt(0)
	s_barrier
	s_mov_b32 s101, m0
	s_mul_i32 s100, s2, 0x180
	v_lshrrev_b32_e32 v24, 2, v1
	v_bfe_u32 v25, v1, 4, 2
	v_lshlrev_b32_e32 v24, 11, v24
	v_xor_b32_e32 v25, v25, v1
	v_bfe_u32 v26, v120, 2, 2
	v_and_b32_e32 v25, 3, v25
	v_xor_b32_e32 v26, v26, v121
	v_lshl_or_b32 v24, v25, 4, v24
	v_lshlrev_b32_e32 v26, 4, v26
	v_lshl_or_b32 v25, v120, 6, v26
	v_add_u32_e32 v25, s100, v25
	v_xor_b32_e32 v26, 32, v25
	s_add_u32 s98, s20, s4
	s_addc_u32 s99, s21, 0
	s_add_i32 m0, s100, 0x0
	s_nop 0
	global_load_lds_dwordx4 v24, s[98:99]
	s_add_u32 s98, s20, s4
	s_addc_u32 s99, s21, 0
	s_add_u32 s98, s98, 0x8000
	s_addc_u32 s99, s99, 0
	s_add_i32 m0, s100, 0x400
	s_nop 0
	global_load_lds_dwordx4 v24, s[98:99]
	s_add_u32 s98, s20, s4
	s_addc_u32 s99, s21, 0
	s_add_u32 s98, s98, 0x10000
	s_addc_u32 s99, s99, 0
	s_add_i32 m0, s100, 0x800
	s_nop 0
	global_load_lds_dwordx4 v24, s[98:99]
	s_add_u32 s98, s20, s4
	s_addc_u32 s99, s21, 0
	s_add_u32 s98, s98, 0x18000
	s_addc_u32 s99, s99, 0
	s_add_i32 m0, s100, 0xc00
	s_nop 0
	global_load_lds_dwordx4 v24, s[98:99]
	s_add_u32 s98, s22, s4
	s_addc_u32 s99, s23, 0
	s_add_u32 s98, s98, 0x2000000
	s_addc_u32 s99, s99, 0
	s_add_i32 m0, s100, 0x1000
	s_nop 0
	global_load_lds_dwordx4 v24, s[98:99]
	s_add_u32 s98, s22, s4
	s_addc_u32 s99, s23, 0
	s_add_u32 s98, s98, 0x2008000
	s_addc_u32 s99, s99, 0
	s_add_i32 m0, s100, 0x1400
	s_nop 0
	global_load_lds_dwordx4 v24, s[98:99]
	s_add_u32 s98, s20, s4
	s_addc_u32 s99, s21, 0
	s_add_u32 s98, s98, 0x40
	s_addc_u32 s99, s99, 0
	s_add_i32 m0, s100, 0x1800
	s_nop 0
	global_load_lds_dwordx4 v24, s[98:99]
	s_add_u32 s98, s20, s4
	s_addc_u32 s99, s21, 0
	s_add_u32 s98, s98, 0x8040
	s_addc_u32 s99, s99, 0
	s_add_i32 m0, s100, 0x1c00
	s_nop 0
	global_load_lds_dwordx4 v24, s[98:99]
	s_add_u32 s98, s20, s4
	s_addc_u32 s99, s21, 0
	s_add_u32 s98, s98, 0x10040
	s_addc_u32 s99, s99, 0
	s_add_i32 m0, s100, 0x2000
	s_nop 0
	global_load_lds_dwordx4 v24, s[98:99]
	s_add_u32 s98, s20, s4
	s_addc_u32 s99, s21, 0
	s_add_u32 s98, s98, 0x18040
	s_addc_u32 s99, s99, 0
	s_add_i32 m0, s100, 0x2400
	s_nop 0
	global_load_lds_dwordx4 v24, s[98:99]
	s_add_u32 s98, s22, s4
	s_addc_u32 s99, s23, 0
	s_add_u32 s98, s98, 0x2000040
	s_addc_u32 s99, s99, 0
	s_add_i32 m0, s100, 0x2800
	s_nop 0
	global_load_lds_dwordx4 v24, s[98:99]
	s_add_u32 s98, s22, s4
	s_addc_u32 s99, s23, 0
	s_add_u32 s98, s98, 0x2008040
	s_addc_u32 s99, s99, 0
	s_add_i32 m0, s100, 0x2c00
	s_nop 0
	global_load_lds_dwordx4 v24, s[98:99]
	s_waitcnt vmcnt(6)
	ds_read_b128 v[10:13], v25
	ds_read_b128 v[2:5], v25 offset:2048
	ds_read_b128 v[6:9], v25 offset:4096
	ds_read_b128 v[36:39], v26
	ds_read_b128 v[40:43], v26 offset:2048
	ds_read_b128 v[104:107], v26 offset:4096
	s_waitcnt lgkmcnt(0)
	s_add_u32 s98, s20, s4
	s_addc_u32 s99, s21, 0
	s_add_u32 s98, s98, 0x80
	s_addc_u32 s99, s99, 0
	s_add_i32 m0, s100, 0x0
	s_nop 0
	global_load_lds_dwordx4 v24, s[98:99]
	s_add_u32 s98, s20, s4
	s_addc_u32 s99, s21, 0
	s_add_u32 s98, s98, 0x8080
	s_addc_u32 s99, s99, 0
	s_add_i32 m0, s100, 0x400
	s_nop 0
	global_load_lds_dwordx4 v24, s[98:99]
	s_add_u32 s98, s20, s4
	s_addc_u32 s99, s21, 0
	s_add_u32 s98, s98, 0x10080
	s_addc_u32 s99, s99, 0
	s_add_i32 m0, s100, 0x800
	s_nop 0
	global_load_lds_dwordx4 v24, s[98:99]
	s_add_u32 s98, s20, s4
	s_addc_u32 s99, s21, 0
	s_add_u32 s98, s98, 0x18080
	s_addc_u32 s99, s99, 0
	s_add_i32 m0, s100, 0xc00
	s_nop 0
	global_load_lds_dwordx4 v24, s[98:99]
	s_add_u32 s98, s22, s4
	s_addc_u32 s99, s23, 0
	s_add_u32 s98, s98, 0x2000080
	s_addc_u32 s99, s99, 0
	s_add_i32 m0, s100, 0x1000
	s_nop 0
	global_load_lds_dwordx4 v24, s[98:99]
	s_add_u32 s98, s22, s4
	s_addc_u32 s99, s23, 0
	s_add_u32 s98, s98, 0x2008080
	s_addc_u32 s99, s99, 0
	s_add_i32 m0, s100, 0x1400
	s_nop 0
	global_load_lds_dwordx4 v24, s[98:99]
	s_waitcnt vmcnt(6)
	ds_read_b128 v[48:51], v25 offset:6144
	ds_read_b128 v[44:47], v25 offset:8192
	ds_read_b128 v[56:59], v25 offset:10240
	ds_read_b128 v[52:55], v26 offset:6144
	ds_read_b128 v[64:67], v26 offset:8192
	ds_read_b128 v[60:63], v26 offset:10240
	s_waitcnt lgkmcnt(0)
	s_add_u32 s98, s20, s4
	s_addc_u32 s99, s21, 0
	s_add_u32 s98, s98, 0xc0
	s_addc_u32 s99, s99, 0
	s_add_i32 m0, s100, 0x1800
	s_nop 0
	global_load_lds_dwordx4 v24, s[98:99]
	s_add_u32 s98, s20, s4
	s_addc_u32 s99, s21, 0
	s_add_u32 s98, s98, 0x80c0
	s_addc_u32 s99, s99, 0
	s_add_i32 m0, s100, 0x1c00
	s_nop 0
	global_load_lds_dwordx4 v24, s[98:99]
	s_add_u32 s98, s20, s4
	s_addc_u32 s99, s21, 0
	s_add_u32 s98, s98, 0x100c0
	s_addc_u32 s99, s99, 0
	s_add_i32 m0, s100, 0x2000
	s_nop 0
	global_load_lds_dwordx4 v24, s[98:99]
	s_add_u32 s98, s20, s4
	s_addc_u32 s99, s21, 0
	s_add_u32 s98, s98, 0x180c0
	s_addc_u32 s99, s99, 0
	s_add_i32 m0, s100, 0x2400
	s_nop 0
	global_load_lds_dwordx4 v24, s[98:99]
	s_add_u32 s98, s22, s4
	s_addc_u32 s99, s23, 0
	s_add_u32 s98, s98, 0x20000c0
	s_addc_u32 s99, s99, 0
	s_add_i32 m0, s100, 0x2800
	s_nop 0
	global_load_lds_dwordx4 v24, s[98:99]
	s_add_u32 s98, s22, s4
	s_addc_u32 s99, s23, 0
	s_add_u32 s98, s98, 0x20080c0
	s_addc_u32 s99, s99, 0
	s_add_i32 m0, s100, 0x2c00
	s_nop 0
	global_load_lds_dwordx4 v24, s[98:99]
	s_waitcnt vmcnt(6)
	ds_read_b128 v[72:75], v25
	ds_read_b128 v[68:71], v25 offset:2048
	ds_read_b128 v[80:83], v25 offset:4096
	ds_read_b128 v[76:79], v26
	ds_read_b128 v[88:91], v26 offset:2048
	ds_read_b128 v[84:87], v26 offset:4096
	s_waitcnt vmcnt(0)
	ds_read_b128 v[96:99], v25 offset:6144
	ds_read_b128 v[92:95], v25 offset:8192
	ds_read_b128 v[112:115], v25 offset:10240
	ds_read_b128 v[100:103], v26 offset:6144
	ds_read_b128 v[108:111], v26 offset:8192
	ds_read_b128 v[116:119], v26 offset:10240
	s_mov_b32 m0, s101
	s_waitcnt lgkmcnt(0)
	v_mfma_f32_32x32x16_bf16 v[18:33], v[10:13], v[6:9], 0
	v_or_b32_e32 v34, s2, v120
	v_mul_lo_u32 v34, v34, s17
	s_and_b64 vcc, exec, s[0:1]
	v_mfma_f32_32x32x16_bf16 v[2:17], v[2:5], v[6:9], 0
	v_mfma_f32_32x32x16_bf16 v[18:33], v[36:39], v[104:107], v[18:33]
	v_lshlrev_b32_e32 v36, 4, v121
	v_add3_u32 v34, 0, v34, v36
	v_mfma_f32_32x32x16_bf16 v[2:17], v[40:43], v[104:107], v[2:17]
	v_mfma_f32_32x32x16_bf16 v[18:33], v[48:51], v[56:59], v[18:33]
	v_mfma_f32_32x32x16_bf16 v[2:17], v[44:47], v[56:59], v[2:17]
	v_mfma_f32_32x32x16_bf16 v[18:33], v[52:55], v[60:63], v[18:33]
	v_mfma_f32_32x32x16_bf16 v[2:17], v[64:67], v[60:63], v[2:17]
	v_mfma_f32_32x32x16_bf16 v[18:33], v[72:75], v[80:83], v[18:33]
	v_mfma_f32_32x32x16_bf16 v[2:17], v[68:71], v[80:83], v[2:17]
	v_mfma_f32_32x32x16_bf16 v[18:33], v[76:79], v[84:87], v[18:33]
	v_mfma_f32_32x32x16_bf16 v[2:17], v[88:91], v[84:87], v[2:17]
	v_mfma_f32_32x32x16_bf16 v[18:33], v[96:99], v[112:115], v[18:33]
	v_mfma_f32_32x32x16_bf16 v[2:17], v[92:95], v[112:115], v[2:17]
	v_mfma_f32_32x32x16_bf16 v[18:33], v[100:103], v[116:119], v[18:33]
	v_mfma_f32_32x32x16_bf16 v[2:17], v[108:111], v[116:119], v[2:17]
	s_nop 10
	s_barrier
	ds_write_b128 v34, v[18:21]
	ds_write_b128 v34, v[2:5] offset:128
	ds_write_b128 v34, v[22:25] offset:32
	ds_write_b128 v34, v[6:9] offset:160
	ds_write_b128 v34, v[26:29] offset:64
	ds_write_b128 v34, v[10:13] offset:192
	ds_write_b128 v34, v[30:33] offset:96
	ds_write_b128 v34, v[14:17] offset:224
	v_add_u32_e32 v2, s14, v1
	v_lshlrev_b32_e32 v1, 2, v1
	v_ashrrev_i32_e32 v36, 4, v2
	v_and_b32_e32 v1, 60, v1
	v_lshlrev_b32_e32 v1, 2, v1
	v_mul_lo_u32 v2, v36, s17
	v_add3_u32 v2, 0, v1, v2
	s_waitcnt lgkmcnt(0)
	s_barrier
	ds_read_b128 v[30:33], v2
	ds_read_b128 v[26:29], v2 offset:8704
	ds_read_b128 v[22:25], v2 offset:17408
	ds_read_b128 v[18:21], v2 offset:26112
	ds_read_b128 v[14:17], v2 offset:34816
	ds_read_b128 v[10:13], v2 offset:43520
	ds_read_b128 v[6:9], v2 offset:52224
	ds_read_b128 v[2:5], v2 offset:60928
	s_waitcnt lgkmcnt(0)
	s_barrier
	s_cbranch_vccnz .LBB0_1243
	s_ashr_i32 s13, s12, 31
	v_ashrrev_i32_e32 v37, 31, v36
	s_lshl_b64 s[12:13], s[12:13], 15
	v_lshlrev_b64 v[36:37], 10, v[36:37]
	v_lshl_add_u64 v[36:37], v[36:37], 0, s[12:13]
	v_lshlrev_b64 v[40:41], 2, v[36:37]
	v_lshl_add_u64 v[36:37], s[42:43], 0, v[40:41]
	v_lshl_or_b32 v34, s19, 8, v1
	v_lshl_add_u64 v[36:37], v[36:37], 0, v[34:35]
	global_load_dwordx4 v[36:39], v[36:37], off
	v_pk_add_f32 v[32:33], v[32:33], 0 op_sel_hi:[1,0]
	v_pk_add_f32 v[30:31], v[30:31], 0 op_sel_hi:[1,0]
	v_pk_add_f32 v[28:29], v[32:33], v[28:29]
	v_pk_add_f32 v[26:27], v[30:31], v[26:27]
	v_pk_add_f32 v[24:25], v[28:29], v[24:25]
	v_pk_add_f32 v[22:23], v[26:27], v[22:23]
	v_pk_add_f32 v[20:21], v[24:25], v[20:21]
	v_pk_add_f32 v[18:19], v[22:23], v[18:19]
	v_pk_add_f32 v[16:17], v[20:21], v[16:17]
	v_pk_add_f32 v[14:15], v[18:19], v[14:15]
	v_pk_add_f32 v[12:13], v[16:17], v[12:13]
	v_pk_add_f32 v[10:11], v[14:15], v[10:11]
	v_pk_add_f32 v[8:9], v[12:13], v[8:9]
	v_pk_add_f32 v[6:7], v[10:11], v[6:7]
	v_lshl_add_u64 v[18:19], s[6:7], 0, v[40:41]
	v_pk_add_f32 v[4:5], v[8:9], v[4:5]
	v_pk_add_f32 v[2:3], v[6:7], v[2:3]
	v_lshl_add_u64 v[6:7], v[18:19], 0, v[34:35]
	s_waitcnt vmcnt(0)
	v_pk_add_f32 v[4:5], v[4:5], v[38:39]
	v_pk_add_f32 v[2:3], v[2:3], v[36:37]
	global_store_dwordx4 v[6:7], v[2:5], off
	s_branch .LBB0_1243

.LBB0_1276:
	s_and_b32 s17, s88, 15
	s_ashr_i32 s10, s88, 4
	s_lshl_b32 s11, s17, 17
	s_add_u32 s18, s44, s11
	v_mov_b32_e32 v118, v228
	s_addc_u32 s19, s45, 0
	s_lshl_b32 s20, s10, 5
	s_ashr_i32 s21, s20, 31
	v_and_b32_e32 v119, 31, v118
	v_ashrrev_i32_e32 v120, 5, v118
	s_lshl_b64 s[20:21], s[20:21], 11
	s_add_u32 s20, s46, s20
	s_addc_u32 s21, s47, s21
	s_waitcnt vmcnt(0) lgkmcnt(0)
	s_barrier
	s_mov_b32 s101, m0
	s_mul_i32 s100, s12, 0x180
	v_lshrrev_b32_e32 v22, 2, v118
	v_bfe_u32 v23, v118, 4, 2
	v_lshlrev_b32_e32 v22, 11, v22
	v_xor_b32_e32 v23, v23, v118
	v_bfe_u32 v24, v119, 2, 2
	v_and_b32_e32 v23, 3, v23
	v_xor_b32_e32 v24, v24, v120
	v_lshl_or_b32 v22, v23, 4, v22
	v_lshlrev_b32_e32 v24, 4, v24
	v_lshl_or_b32 v23, v119, 6, v24
	v_add_u32_e32 v23, s100, v23
	v_xor_b32_e32 v24, 32, v23
	s_add_u32 s98, s18, s2
	s_addc_u32 s99, s19, 0
	s_add_i32 m0, s100, 0x0
	s_nop 0
	global_load_lds_dwordx4 v22, s[98:99]
	s_add_u32 s98, s18, s2
	s_addc_u32 s99, s19, 0
	s_add_u32 s98, s98, 0x8000
	s_addc_u32 s99, s99, 0
	s_add_i32 m0, s100, 0x400
	s_nop 0
	global_load_lds_dwordx4 v22, s[98:99]
	s_add_u32 s98, s18, s2
	s_addc_u32 s99, s19, 0
	s_add_u32 s98, s98, 0x10000
	s_addc_u32 s99, s99, 0
	s_add_i32 m0, s100, 0x800
	s_nop 0
	global_load_lds_dwordx4 v22, s[98:99]
	s_add_u32 s98, s18, s2
	s_addc_u32 s99, s19, 0
	s_add_u32 s98, s98, 0x18000
	s_addc_u32 s99, s99, 0
	s_add_i32 m0, s100, 0xc00
	s_nop 0
	global_load_lds_dwordx4 v22, s[98:99]
	s_add_u32 s98, s20, s2
	s_addc_u32 s99, s21, 0
	s_add_u32 s98, s98, 0x2000000
	s_addc_u32 s99, s99, 0
	s_add_i32 m0, s100, 0x1000
	s_nop 0
	global_load_lds_dwordx4 v22, s[98:99]
	s_add_u32 s98, s20, s2
	s_addc_u32 s99, s21, 0
	s_add_u32 s98, s98, 0x2008000
	s_addc_u32 s99, s99, 0
	s_add_i32 m0, s100, 0x1400
	s_nop 0
	global_load_lds_dwordx4 v22, s[98:99]
	s_add_u32 s98, s18, s2
	s_addc_u32 s99, s19, 0
	s_add_u32 s98, s98, 0x40
	s_addc_u32 s99, s99, 0
	s_add_i32 m0, s100, 0x1800
	s_nop 0
	global_load_lds_dwordx4 v22, s[98:99]
	s_add_u32 s98, s18, s2
	s_addc_u32 s99, s19, 0
	s_add_u32 s98, s98, 0x8040
	s_addc_u32 s99, s99, 0
	s_add_i32 m0, s100, 0x1c00
	s_nop 0
	global_load_lds_dwordx4 v22, s[98:99]
	s_add_u32 s98, s18, s2
	s_addc_u32 s99, s19, 0
	s_add_u32 s98, s98, 0x10040
	s_addc_u32 s99, s99, 0
	s_add_i32 m0, s100, 0x2000
	s_nop 0
	global_load_lds_dwordx4 v22, s[98:99]
	s_add_u32 s98, s18, s2
	s_addc_u32 s99, s19, 0
	s_add_u32 s98, s98, 0x18040
	s_addc_u32 s99, s99, 0
	s_add_i32 m0, s100, 0x2400
	s_nop 0
	global_load_lds_dwordx4 v22, s[98:99]
	s_add_u32 s98, s20, s2
	s_addc_u32 s99, s21, 0
	s_add_u32 s98, s98, 0x2000040
	s_addc_u32 s99, s99, 0
	s_add_i32 m0, s100, 0x2800
	s_nop 0
	global_load_lds_dwordx4 v22, s[98:99]
	s_add_u32 s98, s20, s2
	s_addc_u32 s99, s21, 0
	s_add_u32 s98, s98, 0x2008040
	s_addc_u32 s99, s99, 0
	s_add_i32 m0, s100, 0x2c00
	s_nop 0
	global_load_lds_dwordx4 v22, s[98:99]
	s_waitcnt vmcnt(6)
	ds_read_b128 v[8:11], v23
	ds_read_b128 v[0:3], v23 offset:2048
	ds_read_b128 v[4:7], v23 offset:4096
	ds_read_b128 v[34:37], v24
	ds_read_b128 v[38:41], v24 offset:2048
	ds_read_b128 v[102:105], v24 offset:4096
	s_waitcnt lgkmcnt(0)
	s_add_u32 s98, s18, s2
	s_addc_u32 s99, s19, 0
	s_add_u32 s98, s98, 0x80
	s_addc_u32 s99, s99, 0
	s_add_i32 m0, s100, 0x0
	s_nop 0
	global_load_lds_dwordx4 v22, s[98:99]
	s_add_u32 s98, s18, s2
	s_addc_u32 s99, s19, 0
	s_add_u32 s98, s98, 0x8080
	s_addc_u32 s99, s99, 0
	s_add_i32 m0, s100, 0x400
	s_nop 0
	global_load_lds_dwordx4 v22, s[98:99]
	s_add_u32 s98, s18, s2
	s_addc_u32 s99, s19, 0
	s_add_u32 s98, s98, 0x10080
	s_addc_u32 s99, s99, 0
	s_add_i32 m0, s100, 0x800
	s_nop 0
	global_load_lds_dwordx4 v22, s[98:99]
	s_add_u32 s98, s18, s2
	s_addc_u32 s99, s19, 0
	s_add_u32 s98, s98, 0x18080
	s_addc_u32 s99, s99, 0
	s_add_i32 m0, s100, 0xc00
	s_nop 0
	global_load_lds_dwordx4 v22, s[98:99]
	s_add_u32 s98, s20, s2
	s_addc_u32 s99, s21, 0
	s_add_u32 s98, s98, 0x2000080
	s_addc_u32 s99, s99, 0
	s_add_i32 m0, s100, 0x1000
	s_nop 0
	global_load_lds_dwordx4 v22, s[98:99]
	s_add_u32 s98, s20, s2
	s_addc_u32 s99, s21, 0
	s_add_u32 s98, s98, 0x2008080
	s_addc_u32 s99, s99, 0
	s_add_i32 m0, s100, 0x1400
	s_nop 0
	global_load_lds_dwordx4 v22, s[98:99]
	s_waitcnt vmcnt(6)
	ds_read_b128 v[46:49], v23 offset:6144
	ds_read_b128 v[42:45], v23 offset:8192
	ds_read_b128 v[54:57], v23 offset:10240
	ds_read_b128 v[50:53], v24 offset:6144
	ds_read_b128 v[62:65], v24 offset:8192
	ds_read_b128 v[58:61], v24 offset:10240
	s_waitcnt lgkmcnt(0)
	s_add_u32 s98, s18, s2
	s_addc_u32 s99, s19, 0
	s_add_u32 s98, s98, 0xc0
	s_addc_u32 s99, s99, 0
	s_add_i32 m0, s100, 0x1800
	s_nop 0
	global_load_lds_dwordx4 v22, s[98:99]
	s_add_u32 s98, s18, s2
	s_addc_u32 s99, s19, 0
	s_add_u32 s98, s98, 0x80c0
	s_addc_u32 s99, s99, 0
	s_add_i32 m0, s100, 0x1c00
	s_nop 0
	global_load_lds_dwordx4 v22, s[98:99]
	s_add_u32 s98, s18, s2
	s_addc_u32 s99, s19, 0
	s_add_u32 s98, s98, 0x100c0
	s_addc_u32 s99, s99, 0
	s_add_i32 m0, s100, 0x2000
	s_nop 0
	global_load_lds_dwordx4 v22, s[98:99]
	s_add_u32 s98, s18, s2
	s_addc_u32 s99, s19, 0
	s_add_u32 s98, s98, 0x180c0
	s_addc_u32 s99, s99, 0
	s_add_i32 m0, s100, 0x2400
	s_nop 0
	global_load_lds_dwordx4 v22, s[98:99]
	s_add_u32 s98, s20, s2
	s_addc_u32 s99, s21, 0
	s_add_u32 s98, s98, 0x20000c0
	s_addc_u32 s99, s99, 0
	s_add_i32 m0, s100, 0x2800
	s_nop 0
	global_load_lds_dwordx4 v22, s[98:99]
	s_add_u32 s98, s20, s2
	s_addc_u32 s99, s21, 0
	s_add_u32 s98, s98, 0x20080c0
	s_addc_u32 s99, s99, 0
	s_add_i32 m0, s100, 0x2c00
	s_nop 0
	global_load_lds_dwordx4 v22, s[98:99]
	s_waitcnt vmcnt(6)
	ds_read_b128 v[70:73], v23
	ds_read_b128 v[66:69], v23 offset:2048
	ds_read_b128 v[78:81], v23 offset:4096
	ds_read_b128 v[74:77], v24
	ds_read_b128 v[86:89], v24 offset:2048
	ds_read_b128 v[82:85], v24 offset:4096
	s_waitcnt vmcnt(0)
	ds_read_b128 v[94:97], v23 offset:6144
	ds_read_b128 v[90:93], v23 offset:8192
	ds_read_b128 v[110:113], v23 offset:10240
	ds_read_b128 v[98:101], v24 offset:6144
	ds_read_b128 v[106:109], v24 offset:8192
	ds_read_b128 v[114:117], v24 offset:10240
	s_mov_b32 m0, s101
	s_waitcnt lgkmcnt(0)
	v_mfma_f32_32x32x16_bf16 v[16:31], v[8:11], v[4:7], 0
	v_or_b32_e32 v32, s12, v119
	v_mul_lo_u32 v32, v32, s16
	s_and_b64 vcc, exec, s[0:1]
	v_mfma_f32_32x32x16_bf16 v[0:15], v[0:3], v[4:7], 0
	v_mfma_f32_32x32x16_bf16 v[16:31], v[34:37], v[102:105], v[16:31]
	v_lshlrev_b32_e32 v34, 4, v120
	v_add3_u32 v32, 0, v32, v34
	v_mfma_f32_32x32x16_bf16 v[0:15], v[38:41], v[102:105], v[0:15]
	v_mfma_f32_32x32x16_bf16 v[16:31], v[46:49], v[54:57], v[16:31]
	v_mfma_f32_32x32x16_bf16 v[0:15], v[42:45], v[54:57], v[0:15]
	v_mfma_f32_32x32x16_bf16 v[16:31], v[50:53], v[58:61], v[16:31]
	v_mfma_f32_32x32x16_bf16 v[0:15], v[62:65], v[58:61], v[0:15]
	v_mfma_f32_32x32x16_bf16 v[16:31], v[70:73], v[78:81], v[16:31]
	v_mfma_f32_32x32x16_bf16 v[0:15], v[66:69], v[78:81], v[0:15]
	v_mfma_f32_32x32x16_bf16 v[16:31], v[74:77], v[82:85], v[16:31]
	v_mfma_f32_32x32x16_bf16 v[0:15], v[86:89], v[82:85], v[0:15]
	v_mfma_f32_32x32x16_bf16 v[16:31], v[94:97], v[110:113], v[16:31]
	v_mfma_f32_32x32x16_bf16 v[0:15], v[90:93], v[110:113], v[0:15]
	v_mfma_f32_32x32x16_bf16 v[16:31], v[98:101], v[114:117], v[16:31]
	v_mfma_f32_32x32x16_bf16 v[0:15], v[106:109], v[114:117], v[0:15]
	s_nop 10
	s_barrier
	ds_write_b128 v32, v[16:19]
	ds_write_b128 v32, v[0:3] offset:128
	ds_write_b128 v32, v[20:23] offset:32
	ds_write_b128 v32, v[4:7] offset:160
	ds_write_b128 v32, v[24:27] offset:64
	ds_write_b128 v32, v[8:11] offset:192
	ds_write_b128 v32, v[28:31] offset:96
	ds_write_b128 v32, v[12:15] offset:224
	v_add_u32_e32 v0, s13, v118
	v_ashrrev_i32_e32 v34, 4, v0
	v_lshlrev_b32_e32 v0, 2, v118
	v_and_b32_e32 v0, 60, v0
	v_lshlrev_b32_e32 v32, 2, v0
	v_mul_lo_u32 v0, v34, s16
	v_add3_u32 v0, 0, v32, v0
	s_waitcnt lgkmcnt(0)
	s_barrier
	ds_read_b128 v[28:31], v0
	ds_read_b128 v[24:27], v0 offset:8704
	ds_read_b128 v[20:23], v0 offset:17408
	ds_read_b128 v[16:19], v0 offset:26112
	ds_read_b128 v[12:15], v0 offset:34816
	ds_read_b128 v[8:11], v0 offset:43520
	ds_read_b128 v[4:7], v0 offset:52224
	ds_read_b128 v[0:3], v0 offset:60928
	s_waitcnt lgkmcnt(0)
	s_barrier
	s_cbranch_vccnz .LBB0_1275
	s_ashr_i32 s11, s10, 31
	v_ashrrev_i32_e32 v35, 31, v34
	s_lshl_b64 s[10:11], s[10:11], 15
	v_lshlrev_b64 v[34:35], 10, v[34:35]
	v_lshl_add_u64 v[34:35], v[34:35], 0, s[10:11]
	v_lshlrev_b64 v[38:39], 2, v[34:35]
	v_lshl_add_u64 v[34:35], s[42:43], 0, v[38:39]
	v_lshl_or_b32 v32, s17, 8, v32
	v_lshl_add_u64 v[34:35], v[34:35], 0, v[32:33]
	global_load_dwordx4 v[34:37], v[34:35], off
	v_pk_add_f32 v[30:31], v[30:31], 0 op_sel_hi:[1,0]
	v_pk_add_f32 v[28:29], v[28:29], 0 op_sel_hi:[1,0]
	v_pk_add_f32 v[26:27], v[30:31], v[26:27]
	v_pk_add_f32 v[24:25], v[28:29], v[24:25]
	v_pk_add_f32 v[22:23], v[26:27], v[22:23]
	v_pk_add_f32 v[20:21], v[24:25], v[20:21]
	v_pk_add_f32 v[18:19], v[22:23], v[18:19]
	v_pk_add_f32 v[16:17], v[20:21], v[16:17]
	v_pk_add_f32 v[14:15], v[18:19], v[14:15]
	v_pk_add_f32 v[12:13], v[16:17], v[12:13]
	v_pk_add_f32 v[10:11], v[14:15], v[10:11]
	v_pk_add_f32 v[8:9], v[12:13], v[8:9]
	v_pk_add_f32 v[6:7], v[10:11], v[6:7]
	v_pk_add_f32 v[4:5], v[8:9], v[4:5]
	v_lshl_add_u64 v[16:17], s[4:5], 0, v[38:39]
	v_pk_add_f32 v[2:3], v[6:7], v[2:3]
	v_pk_add_f32 v[0:1], v[4:5], v[0:1]
	v_lshl_add_u64 v[4:5], v[16:17], 0, v[32:33]
	s_waitcnt vmcnt(0)
	v_pk_add_f32 v[2:3], v[2:3], v[36:37]
	v_pk_add_f32 v[0:1], v[0:1], v[34:35]
	global_store_dwordx4 v[4:5], v[0:3], off
	s_branch .LBB0_1275
